# v72 + FF-IN activation tile stores carry the nt (streaming) hint in addition to sc1: the 184 MB act buffer is written once and read once in the next phase
# speedup vs baseline: 1.0015x; 1.0015x over previous
;     __device__ __forceinline__ void operator()(const f32x4 (&acc)[2][2][4][2], const Unit& u, int wr, int wc, int fr, int fq) const {
;     ...
;             for (int m = 0; m < 4; ++m) {
;                 const int row = row0 + ai * HALF + m * 16; const float rs = rsv[m];
;                 const f32x4 ca = acc[ai][0][m][0] * rs, cb_ = acc[ai][0][m][1] * rs;
;                 f32x4 aa = w2a * ca + ba, ab = w2b * cb_ + bb;
; #pragma unroll
;                 for (int c = 0; c < 4; ++c) { aa[c] = __builtin_fmaf(w1a[c], dpp_shr1(ca[c]), aa[c]); ab[c] = __builtin_fmaf(w1b[c], dpp_shr1(cb_[c]), ab[c]);
;                     aa[c] = __builtin_fmaf(w0a[c], dpp_shr2(ca[c]), aa[c]); ab[c] = __builtin_fmaf(w0b[c], dpp_shr2(cb_[c]), ab[c]); }
;                 if (m == 0) {
;                     if (ai == 1 || wr == 1) { const int sw = ((ai == 1 && wr == 0) ? 4 : 0) + wc, sai = (ai == 1 && wr == 1) ? 1 : 0;
;                         const PG8_LAS f32x4* xp = (const PG8_LAS f32x4*)(X + ((sw * 2 + sai) * 2) * 32 + fq * 8); const f32x4 h0a = xp[0], h0b = xp[1], h1a = xp[8], h1b = xp[9];
;                         aa += w1a * (h1a * m0) + w0a * (h0a * m0 + h1a * m1); ab += w1b * (h1b * m0) + w0b * (h0b * m0 + h1b * m1); }
;                 } else {
; #pragma unroll
;                     for (int c = 0; c < 4; ++c) { aa[c] = __builtin_fmaf(w1a[c], dpp_shl15(pa[c]), aa[c]); ab[c] = __builtin_fmaf(w1b[c], dpp_shl15(pb[c]), ab[c]);
;                         aa[c] = __builtin_fmaf(w0a[c], dpp_shl14(pa[c]), aa[c]); ab[c] = __builtin_fmaf(w0b[c], dpp_shl14(pb[c]), ab[c]); }
;                 }
;                 const f32x4 ga = acc[ai][1][m][0] * rs, gb = acc[ai][1][m][1] * rs;
;                 f32x4 ea = aa * -1.4426950408889634f, eb = ab * -1.4426950408889634f;
; #pragma unroll
;                 for (int c = 0; c < 4; ++c) { ea[c] = __builtin_amdgcn_exp2f(ea[c]); eb[c] = __builtin_amdgcn_exp2f(eb[c]); }
;                 ea = ea + 1.0f; eb = eb + 1.0f;
; #pragma unroll
;                 for (int c = 0; c < 4; ++c) { ea[c] = __builtin_amdgcn_rcpf(ea[c]); eb[c] = __builtin_amdgcn_rcpf(eb[c]); }
;                 const f32x4 oa = (aa * ga) * ea, ob = (ab * gb) * eb;
;                 u32x4 w; w.x = cvt_pk_bf16(oa[0], oa[1]); w.y = cvt_pk_bf16(oa[2], oa[3]); w.z = cvt_pk_bf16(ob[0], ob[1]); w.w = cvt_pk_bf16(ob[2], ob[3]);
;                 *(u32x4*)(act + (size_t)row * FF + col) = w;
.Lffin_nopark:
	s_or_b64 exec, exec, s[46:47]
	v_pk_mul_f32 v[244:245], v[236:237], s[92:93] op_sel_hi:[1,0]
	v_pk_mul_f32 v[246:247], v[238:239], s[92:93] op_sel_hi:[1,0]
	v_pk_mul_f32 v[248:249], v[240:241], s[92:93] op_sel_hi:[1,0]
	v_pk_mul_f32 v[250:251], v[242:243], s[92:93] op_sel_hi:[1,0]
	v_exp_f32_e32 v244, v244
	v_exp_f32_e32 v245, v245
	v_exp_f32_e32 v246, v246
	v_exp_f32_e32 v247, v247
	v_exp_f32_e32 v248, v248
	v_exp_f32_e32 v249, v249
	v_exp_f32_e32 v250, v250
	v_exp_f32_e32 v251, v251
	v_pk_mul_f32 v[236:237], v[236:237], v[150:151]
	v_pk_mul_f32 v[238:239], v[238:239], v[152:153]
	v_pk_mul_f32 v[240:241], v[240:241], v[146:147]
	v_pk_mul_f32 v[242:243], v[242:243], v[148:149]
	v_pk_add_f32 v[244:245], v[244:245], 1.0 op_sel_hi:[1,0]
	v_pk_add_f32 v[246:247], v[246:247], 1.0 op_sel_hi:[1,0]
	v_pk_add_f32 v[248:249], v[248:249], 1.0 op_sel_hi:[1,0]
	v_pk_add_f32 v[250:251], v[250:251], 1.0 op_sel_hi:[1,0]
	v_rcp_f32_e32 v244, v244
	v_rcp_f32_e32 v245, v245
	v_rcp_f32_e32 v246, v246
	v_rcp_f32_e32 v247, v247
	v_rcp_f32_e32 v248, v248
	v_rcp_f32_e32 v249, v249
	v_rcp_f32_e32 v250, v250
	v_rcp_f32_e32 v251, v251
	s_nop 0
	v_pk_mul_f32 v[236:237], v[236:237], v[244:245]
	v_pk_mul_f32 v[238:239], v[238:239], v[246:247]
	v_pk_mul_f32 v[240:241], v[240:241], v[248:249]
	v_pk_mul_f32 v[242:243], v[242:243], v[250:251]
	v_cvt_pk_bf16_f32 v216, v236, v237
	v_cvt_pk_bf16_f32 v217, v238, v239
	v_cvt_pk_bf16_f32 v218, v240, v241
	v_cvt_pk_bf16_f32 v219, v242, v243
	global_store_dwordx4 v[220:221], v[216:219], off sc1 nt
	v_lshl_add_u64 v[220:221], v[220:221], 0, s[100:101]
	v_pk_mul_f32 v[142:143], v[142:143], v[164:165] op_sel_hi:[1,0]
	v_pk_mul_f32 v[144:145], v[144:145], v[164:165] op_sel_hi:[1,0]
	v_pk_mul_f32 v[138:139], v[138:139], v[164:165] op_sel_hi:[1,0]
	v_pk_mul_f32 v[140:141], v[140:141], v[164:165] op_sel_hi:[1,0]
	v_pk_fma_f32 v[236:237], v[122:123], v[142:143], v[130:131]
	v_pk_fma_f32 v[238:239], v[124:125], v[144:145], v[132:133]
	v_pk_fma_f32 v[240:241], v[126:127], v[138:139], v[134:135]
	v_pk_fma_f32 v[242:243], v[128:129], v[140:141], v[136:137]
	v_pk_mul_f32 v[102:103], v[102:103], v[164:165] op_sel_hi:[1,0]
	v_pk_mul_f32 v[104:105], v[104:105], v[164:165] op_sel_hi:[1,0]
	v_pk_mul_f32 v[98:99], v[98:99], v[164:165] op_sel_hi:[1,0]
	v_pk_mul_f32 v[100:101], v[100:101], v[164:165] op_sel_hi:[1,0]
	v_fmac_f32_dpp v236, v142, v114 row_shr:1 row_mask:0xf bank_mask:0xf bound_ctrl:1
	v_fmac_f32_dpp v237, v143, v115 row_shr:1 row_mask:0xf bank_mask:0xf bound_ctrl:1
	v_fmac_f32_dpp v238, v144, v116 row_shr:1 row_mask:0xf bank_mask:0xf bound_ctrl:1
	v_fmac_f32_dpp v239, v145, v117 row_shr:1 row_mask:0xf bank_mask:0xf bound_ctrl:1
	v_fmac_f32_dpp v240, v138, v118 row_shr:1 row_mask:0xf bank_mask:0xf bound_ctrl:1
	v_fmac_f32_dpp v241, v139, v119 row_shr:1 row_mask:0xf bank_mask:0xf bound_ctrl:1
	v_fmac_f32_dpp v242, v140, v120 row_shr:1 row_mask:0xf bank_mask:0xf bound_ctrl:1
	v_fmac_f32_dpp v243, v141, v121 row_shr:1 row_mask:0xf bank_mask:0xf bound_ctrl:1
	v_fmac_f32_dpp v236, v142, v106 row_shr:2 row_mask:0xf bank_mask:0xf bound_ctrl:1
	v_fmac_f32_dpp v237, v143, v107 row_shr:2 row_mask:0xf bank_mask:0xf bound_ctrl:1
	v_fmac_f32_dpp v238, v144, v108 row_shr:2 row_mask:0xf bank_mask:0xf bound_ctrl:1
	v_fmac_f32_dpp v239, v145, v109 row_shr:2 row_mask:0xf bank_mask:0xf bound_ctrl:1
	v_fmac_f32_dpp v240, v138, v110 row_shr:2 row_mask:0xf bank_mask:0xf bound_ctrl:1
	v_fmac_f32_dpp v241, v139, v111 row_shr:2 row_mask:0xf bank_mask:0xf bound_ctrl:1
	v_fmac_f32_dpp v242, v140, v112 row_shr:2 row_mask:0xf bank_mask:0xf bound_ctrl:1
	v_fmac_f32_dpp v243, v141, v113 row_shr:2 row_mask:0xf bank_mask:0xf bound_ctrl:1
	v_fmac_f32_dpp v236, v158, v114 row_shl:15 row_mask:0xf bank_mask:0xf bound_ctrl:1
	v_fmac_f32_dpp v237, v159, v115 row_shl:15 row_mask:0xf bank_mask:0xf bound_ctrl:1
	v_fmac_f32_dpp v238, v160, v116 row_shl:15 row_mask:0xf bank_mask:0xf bound_ctrl:1
	v_fmac_f32_dpp v239, v161, v117 row_shl:15 row_mask:0xf bank_mask:0xf bound_ctrl:1
	v_fmac_f32_dpp v240, v154, v118 row_shl:15 row_mask:0xf bank_mask:0xf bound_ctrl:1
	v_fmac_f32_dpp v241, v155, v119 row_shl:15 row_mask:0xf bank_mask:0xf bound_ctrl:1
	v_fmac_f32_dpp v242, v156, v120 row_shl:15 row_mask:0xf bank_mask:0xf bound_ctrl:1
	v_fmac_f32_dpp v243, v157, v121 row_shl:15 row_mask:0xf bank_mask:0xf bound_ctrl:1
	v_fmac_f32_dpp v236, v158, v106 row_shl:14 row_mask:0xf bank_mask:0xf bound_ctrl:1
	v_fmac_f32_dpp v237, v159, v107 row_shl:14 row_mask:0xf bank_mask:0xf bound_ctrl:1
	v_fmac_f32_dpp v238, v160, v108 row_shl:14 row_mask:0xf bank_mask:0xf bound_ctrl:1
	v_fmac_f32_dpp v239, v161, v109 row_shl:14 row_mask:0xf bank_mask:0xf bound_ctrl:1
	v_fmac_f32_dpp v240, v154, v110 row_shl:14 row_mask:0xf bank_mask:0xf bound_ctrl:1
	v_fmac_f32_dpp v241, v155, v111 row_shl:14 row_mask:0xf bank_mask:0xf bound_ctrl:1
	v_fmac_f32_dpp v242, v156, v112 row_shl:14 row_mask:0xf bank_mask:0xf bound_ctrl:1
	v_fmac_f32_dpp v243, v157, v113 row_shl:14 row_mask:0xf bank_mask:0xf bound_ctrl:1
	v_pk_mul_f32 v[244:245], v[236:237], s[92:93] op_sel_hi:[1,0]
	v_pk_mul_f32 v[246:247], v[238:239], s[92:93] op_sel_hi:[1,0]
	v_pk_mul_f32 v[248:249], v[240:241], s[92:93] op_sel_hi:[1,0]
	v_pk_mul_f32 v[250:251], v[242:243], s[92:93] op_sel_hi:[1,0]
	v_exp_f32_e32 v244, v244
	v_exp_f32_e32 v245, v245
	v_exp_f32_e32 v246, v246
	v_exp_f32_e32 v247, v247
	v_exp_f32_e32 v248, v248
	v_exp_f32_e32 v249, v249
	v_exp_f32_e32 v250, v250
	v_exp_f32_e32 v251, v251
	v_pk_mul_f32 v[236:237], v[236:237], v[102:103]
	v_pk_mul_f32 v[238:239], v[238:239], v[104:105]
	v_pk_mul_f32 v[240:241], v[240:241], v[98:99]
;     __device__ __forceinline__ void operator()(const f32x4 (&acc)[2][2][4][2], const Unit& u, int wr, int wc, int fr, int fq) const {
;     ...
;             for (int m = 0; m < 4; ++m) {
;                 const int row = row0 + ai * HALF + m * 16; const float rs = rsv[m];
;                 const f32x4 ca = acc[ai][0][m][0] * rs, cb_ = acc[ai][0][m][1] * rs;
;                 f32x4 aa = w2a * ca + ba, ab = w2b * cb_ + bb;
; #pragma unroll
;                 for (int c = 0; c < 4; ++c) { aa[c] = __builtin_fmaf(w1a[c], dpp_shr1(ca[c]), aa[c]); ab[c] = __builtin_fmaf(w1b[c], dpp_shr1(cb_[c]), ab[c]);
;                     aa[c] = __builtin_fmaf(w0a[c], dpp_shr2(ca[c]), aa[c]); ab[c] = __builtin_fmaf(w0b[c], dpp_shr2(cb_[c]), ab[c]); }
;                 if (m == 0) {
;                     if (ai == 1 || wr == 1) { const int sw = ((ai == 1 && wr == 0) ? 4 : 0) + wc, sai = (ai == 1 && wr == 1) ? 1 : 0;
;                         const PG8_LAS f32x4* xp = (const PG8_LAS f32x4*)(X + ((sw * 2 + sai) * 2) * 32 + fq * 8); const f32x4 h0a = xp[0], h0b = xp[1], h1a = xp[8], h1b = xp[9];
;                         aa += w1a * (h1a * m0) + w0a * (h0a * m0 + h1a * m1); ab += w1b * (h1b * m0) + w0b * (h0b * m0 + h1b * m1); }
;                 } else {
; #pragma unroll
;                     for (int c = 0; c < 4; ++c) { aa[c] = __builtin_fmaf(w1a[c], dpp_shl15(pa[c]), aa[c]); ab[c] = __builtin_fmaf(w1b[c], dpp_shl15(pb[c]), ab[c]);
;                         aa[c] = __builtin_fmaf(w0a[c], dpp_shl14(pa[c]), aa[c]); ab[c] = __builtin_fmaf(w0b[c], dpp_shl14(pb[c]), ab[c]); }
;                 }
;                 const f32x4 ga = acc[ai][1][m][0] * rs, gb = acc[ai][1][m][1] * rs;
;                 f32x4 ea = aa * -1.4426950408889634f, eb = ab * -1.4426950408889634f;
; #pragma unroll
;                 for (int c = 0; c < 4; ++c) { ea[c] = __builtin_amdgcn_exp2f(ea[c]); eb[c] = __builtin_amdgcn_exp2f(eb[c]); }
;                 ea = ea + 1.0f; eb = eb + 1.0f;
; #pragma unroll
;                 for (int c = 0; c < 4; ++c) { ea[c] = __builtin_amdgcn_rcpf(ea[c]); eb[c] = __builtin_amdgcn_rcpf(eb[c]); }
;                 const f32x4 oa = (aa * ga) * ea, ob = (ab * gb) * eb;
;                 u32x4 w; w.x = cvt_pk_bf16(oa[0], oa[1]); w.y = cvt_pk_bf16(oa[2], oa[3]); w.z = cvt_pk_bf16(ob[0], ob[1]); w.w = cvt_pk_bf16(ob[2], ob[3]);
;                 *(u32x4*)(act + (size_t)row * FF + col) = w;
	v_pk_mul_f32 v[242:243], v[242:243], v[100:101]
	v_pk_add_f32 v[244:245], v[244:245], 1.0 op_sel_hi:[1,0]
	v_pk_add_f32 v[246:247], v[246:247], 1.0 op_sel_hi:[1,0]
	v_pk_add_f32 v[248:249], v[248:249], 1.0 op_sel_hi:[1,0]
	v_pk_add_f32 v[250:251], v[250:251], 1.0 op_sel_hi:[1,0]
	v_rcp_f32_e32 v244, v244
	v_rcp_f32_e32 v245, v245
	v_rcp_f32_e32 v246, v246
	v_rcp_f32_e32 v247, v247
	v_rcp_f32_e32 v248, v248
	v_rcp_f32_e32 v249, v249
	v_rcp_f32_e32 v250, v250
	v_rcp_f32_e32 v251, v251
	s_nop 0
	v_pk_mul_f32 v[236:237], v[236:237], v[244:245]
	v_pk_mul_f32 v[238:239], v[238:239], v[246:247]
	v_pk_mul_f32 v[240:241], v[240:241], v[248:249]
	v_pk_mul_f32 v[242:243], v[242:243], v[250:251]
	v_cvt_pk_bf16_f32 v216, v236, v237
	v_cvt_pk_bf16_f32 v217, v238, v239
	v_cvt_pk_bf16_f32 v218, v240, v241
	v_cvt_pk_bf16_f32 v219, v242, v243
	global_store_dwordx4 v[220:221], v[216:219], off sc1 nt
	v_lshl_add_u64 v[220:221], v[220:221], 0, s[100:101]
	v_pk_mul_f32 v[94:95], v[94:95], v[166:167] op_sel_hi:[1,0]
	v_pk_mul_f32 v[96:97], v[96:97], v[166:167] op_sel_hi:[1,0]
	v_pk_mul_f32 v[90:91], v[90:91], v[166:167] op_sel_hi:[1,0]
	v_pk_mul_f32 v[92:93], v[92:93], v[166:167] op_sel_hi:[1,0]
	v_pk_fma_f32 v[236:237], v[122:123], v[94:95], v[130:131]
	v_pk_fma_f32 v[238:239], v[124:125], v[96:97], v[132:133]
	v_pk_fma_f32 v[240:241], v[126:127], v[90:91], v[134:135]
	v_pk_fma_f32 v[242:243], v[128:129], v[92:93], v[136:137]
	v_pk_mul_f32 v[86:87], v[86:87], v[166:167] op_sel_hi:[1,0]
	v_pk_mul_f32 v[88:89], v[88:89], v[166:167] op_sel_hi:[1,0]
	v_pk_mul_f32 v[82:83], v[82:83], v[166:167] op_sel_hi:[1,0]
	v_pk_mul_f32 v[84:85], v[84:85], v[166:167] op_sel_hi:[1,0]
	v_fmac_f32_dpp v236, v94, v114 row_shr:1 row_mask:0xf bank_mask:0xf bound_ctrl:1
	v_fmac_f32_dpp v237, v95, v115 row_shr:1 row_mask:0xf bank_mask:0xf bound_ctrl:1
	v_fmac_f32_dpp v238, v96, v116 row_shr:1 row_mask:0xf bank_mask:0xf bound_ctrl:1
	v_fmac_f32_dpp v239, v97, v117 row_shr:1 row_mask:0xf bank_mask:0xf bound_ctrl:1
	v_fmac_f32_dpp v240, v90, v118 row_shr:1 row_mask:0xf bank_mask:0xf bound_ctrl:1
	v_fmac_f32_dpp v241, v91, v119 row_shr:1 row_mask:0xf bank_mask:0xf bound_ctrl:1
	v_fmac_f32_dpp v242, v92, v120 row_shr:1 row_mask:0xf bank_mask:0xf bound_ctrl:1
	v_fmac_f32_dpp v243, v93, v121 row_shr:1 row_mask:0xf bank_mask:0xf bound_ctrl:1
	v_fmac_f32_dpp v236, v94, v106 row_shr:2 row_mask:0xf bank_mask:0xf bound_ctrl:1
	v_fmac_f32_dpp v237, v95, v107 row_shr:2 row_mask:0xf bank_mask:0xf bound_ctrl:1
	v_fmac_f32_dpp v238, v96, v108 row_shr:2 row_mask:0xf bank_mask:0xf bound_ctrl:1
	v_fmac_f32_dpp v239, v97, v109 row_shr:2 row_mask:0xf bank_mask:0xf bound_ctrl:1
	v_fmac_f32_dpp v240, v90, v110 row_shr:2 row_mask:0xf bank_mask:0xf bound_ctrl:1
	v_fmac_f32_dpp v241, v91, v111 row_shr:2 row_mask:0xf bank_mask:0xf bound_ctrl:1
	v_fmac_f32_dpp v242, v92, v112 row_shr:2 row_mask:0xf bank_mask:0xf bound_ctrl:1
	v_fmac_f32_dpp v243, v93, v113 row_shr:2 row_mask:0xf bank_mask:0xf bound_ctrl:1
	v_fmac_f32_dpp v236, v142, v114 row_shl:15 row_mask:0xf bank_mask:0xf bound_ctrl:1
	v_fmac_f32_dpp v237, v143, v115 row_shl:15 row_mask:0xf bank_mask:0xf bound_ctrl:1
	v_fmac_f32_dpp v238, v144, v116 row_shl:15 row_mask:0xf bank_mask:0xf bound_ctrl:1
	v_fmac_f32_dpp v239, v145, v117 row_shl:15 row_mask:0xf bank_mask:0xf bound_ctrl:1
	v_fmac_f32_dpp v240, v138, v118 row_shl:15 row_mask:0xf bank_mask:0xf bound_ctrl:1
	v_fmac_f32_dpp v241, v139, v119 row_shl:15 row_mask:0xf bank_mask:0xf bound_ctrl:1
	v_fmac_f32_dpp v242, v140, v120 row_shl:15 row_mask:0xf bank_mask:0xf bound_ctrl:1
	v_fmac_f32_dpp v243, v141, v121 row_shl:15 row_mask:0xf bank_mask:0xf bound_ctrl:1
	v_fmac_f32_dpp v236, v142, v106 row_shl:14 row_mask:0xf bank_mask:0xf bound_ctrl:1
	v_fmac_f32_dpp v237, v143, v107 row_shl:14 row_mask:0xf bank_mask:0xf bound_ctrl:1
	v_fmac_f32_dpp v238, v144, v108 row_shl:14 row_mask:0xf bank_mask:0xf bound_ctrl:1
	v_fmac_f32_dpp v239, v145, v109 row_shl:14 row_mask:0xf bank_mask:0xf bound_ctrl:1
	v_fmac_f32_dpp v240, v138, v110 row_shl:14 row_mask:0xf bank_mask:0xf bound_ctrl:1
	v_fmac_f32_dpp v241, v139, v111 row_shl:14 row_mask:0xf bank_mask:0xf bound_ctrl:1
	v_fmac_f32_dpp v242, v140, v112 row_shl:14 row_mask:0xf bank_mask:0xf bound_ctrl:1
	v_fmac_f32_dpp v243, v141, v113 row_shl:14 row_mask:0xf bank_mask:0xf bound_ctrl:1
	v_pk_mul_f32 v[244:245], v[236:237], s[92:93] op_sel_hi:[1,0]
	v_pk_mul_f32 v[246:247], v[238:239], s[92:93] op_sel_hi:[1,0]
	v_pk_mul_f32 v[248:249], v[240:241], s[92:93] op_sel_hi:[1,0]
	v_pk_mul_f32 v[250:251], v[242:243], s[92:93] op_sel_hi:[1,0]
	v_exp_f32_e32 v244, v244
	v_exp_f32_e32 v245, v245
	v_exp_f32_e32 v246, v246
	v_exp_f32_e32 v247, v247
	v_exp_f32_e32 v248, v248
	v_exp_f32_e32 v249, v249
	v_exp_f32_e32 v250, v250
	v_exp_f32_e32 v251, v251
	v_pk_mul_f32 v[236:237], v[236:237], v[86:87]
	v_pk_mul_f32 v[238:239], v[238:239], v[88:89]
	v_pk_mul_f32 v[240:241], v[240:241], v[82:83]
	v_pk_mul_f32 v[242:243], v[242:243], v[84:85]
	v_pk_add_f32 v[244:245], v[244:245], 1.0 op_sel_hi:[1,0]
	v_pk_add_f32 v[246:247], v[246:247], 1.0 op_sel_hi:[1,0]
	v_pk_add_f32 v[248:249], v[248:249], 1.0 op_sel_hi:[1,0]
	v_pk_add_f32 v[250:251], v[250:251], 1.0 op_sel_hi:[1,0]
	v_rcp_f32_e32 v244, v244
	v_rcp_f32_e32 v245, v245
	v_rcp_f32_e32 v246, v246
	v_rcp_f32_e32 v247, v247
	v_rcp_f32_e32 v248, v248
	v_rcp_f32_e32 v249, v249
	v_rcp_f32_e32 v250, v250
	v_rcp_f32_e32 v251, v251
	s_nop 0
	v_pk_mul_f32 v[236:237], v[236:237], v[244:245]
	v_pk_mul_f32 v[238:239], v[238:239], v[246:247]
	v_pk_mul_f32 v[240:241], v[240:241], v[248:249]
	v_pk_mul_f32 v[242:243], v[242:243], v[250:251]
;     __device__ __forceinline__ void operator()(const f32x4 (&acc)[2][2][4][2], const Unit& u, int wr, int wc, int fr, int fq) const {
;     ...
;             for (int m = 0; m < 4; ++m) {
;                 const int row = row0 + ai * HALF + m * 16; const float rs = rsv[m];
;                 const f32x4 ca = acc[ai][0][m][0] * rs, cb_ = acc[ai][0][m][1] * rs;
;                 f32x4 aa = w2a * ca + ba, ab = w2b * cb_ + bb;
; #pragma unroll
;                 for (int c = 0; c < 4; ++c) { aa[c] = __builtin_fmaf(w1a[c], dpp_shr1(ca[c]), aa[c]); ab[c] = __builtin_fmaf(w1b[c], dpp_shr1(cb_[c]), ab[c]);
;                     aa[c] = __builtin_fmaf(w0a[c], dpp_shr2(ca[c]), aa[c]); ab[c] = __builtin_fmaf(w0b[c], dpp_shr2(cb_[c]), ab[c]); }
;                 if (m == 0) {
;                     if (ai == 1 || wr == 1) { const int sw = ((ai == 1 && wr == 0) ? 4 : 0) + wc, sai = (ai == 1 && wr == 1) ? 1 : 0;
;                         const PG8_LAS f32x4* xp = (const PG8_LAS f32x4*)(X + ((sw * 2 + sai) * 2) * 32 + fq * 8); const f32x4 h0a = xp[0], h0b = xp[1], h1a = xp[8], h1b = xp[9];
;                         aa += w1a * (h1a * m0) + w0a * (h0a * m0 + h1a * m1); ab += w1b * (h1b * m0) + w0b * (h0b * m0 + h1b * m1); }
;                 } else {
; #pragma unroll
;                     for (int c = 0; c < 4; ++c) { aa[c] = __builtin_fmaf(w1a[c], dpp_shl15(pa[c]), aa[c]); ab[c] = __builtin_fmaf(w1b[c], dpp_shl15(pb[c]), ab[c]);
;                         aa[c] = __builtin_fmaf(w0a[c], dpp_shl14(pa[c]), aa[c]); ab[c] = __builtin_fmaf(w0b[c], dpp_shl14(pb[c]), ab[c]); }
;                 }
;                 const f32x4 ga = acc[ai][1][m][0] * rs, gb = acc[ai][1][m][1] * rs;
;                 f32x4 ea = aa * -1.4426950408889634f, eb = ab * -1.4426950408889634f;
; #pragma unroll
;                 for (int c = 0; c < 4; ++c) { ea[c] = __builtin_amdgcn_exp2f(ea[c]); eb[c] = __builtin_amdgcn_exp2f(eb[c]); }
;                 ea = ea + 1.0f; eb = eb + 1.0f;
; #pragma unroll
;                 for (int c = 0; c < 4; ++c) { ea[c] = __builtin_amdgcn_rcpf(ea[c]); eb[c] = __builtin_amdgcn_rcpf(eb[c]); }
;                 const f32x4 oa = (aa * ga) * ea, ob = (ab * gb) * eb;
;                 u32x4 w; w.x = cvt_pk_bf16(oa[0], oa[1]); w.y = cvt_pk_bf16(oa[2], oa[3]); w.z = cvt_pk_bf16(ob[0], ob[1]); w.w = cvt_pk_bf16(ob[2], ob[3]);
;                 *(u32x4*)(act + (size_t)row * FF + col) = w;
	v_cvt_pk_bf16_f32 v216, v236, v237
	v_cvt_pk_bf16_f32 v217, v238, v239
	v_cvt_pk_bf16_f32 v218, v240, v241
	v_cvt_pk_bf16_f32 v219, v242, v243
	global_store_dwordx4 v[220:221], v[216:219], off sc1 nt
	v_lshl_add_u64 v[220:221], v[220:221], 0, s[100:101]
	v_pk_fma_f32 v[236:237], v[122:123], v[78:79], v[130:131]
	v_pk_fma_f32 v[238:239], v[124:125], v[80:81], v[132:133]
	v_pk_fma_f32 v[240:241], v[126:127], v[74:75], v[134:135]
	v_pk_fma_f32 v[242:243], v[128:129], v[76:77], v[136:137]
	v_pk_mul_f32 v[70:71], v[70:71], v[168:169] op_sel_hi:[1,0]
	v_pk_mul_f32 v[72:73], v[72:73], v[168:169] op_sel_hi:[1,0]
	v_pk_mul_f32 v[66:67], v[66:67], v[168:169] op_sel_hi:[1,0]
	v_pk_mul_f32 v[68:69], v[68:69], v[168:169] op_sel_hi:[1,0]
	v_fmac_f32_dpp v236, v78, v114 row_shr:1 row_mask:0xf bank_mask:0xf bound_ctrl:1
	v_fmac_f32_dpp v237, v79, v115 row_shr:1 row_mask:0xf bank_mask:0xf bound_ctrl:1
	v_fmac_f32_dpp v238, v80, v116 row_shr:1 row_mask:0xf bank_mask:0xf bound_ctrl:1
	v_fmac_f32_dpp v239, v81, v117 row_shr:1 row_mask:0xf bank_mask:0xf bound_ctrl:1
	v_fmac_f32_dpp v240, v74, v118 row_shr:1 row_mask:0xf bank_mask:0xf bound_ctrl:1
	v_fmac_f32_dpp v241, v75, v119 row_shr:1 row_mask:0xf bank_mask:0xf bound_ctrl:1
	v_fmac_f32_dpp v242, v76, v120 row_shr:1 row_mask:0xf bank_mask:0xf bound_ctrl:1
	v_fmac_f32_dpp v243, v77, v121 row_shr:1 row_mask:0xf bank_mask:0xf bound_ctrl:1
	v_fmac_f32_dpp v236, v78, v106 row_shr:2 row_mask:0xf bank_mask:0xf bound_ctrl:1
	v_fmac_f32_dpp v237, v79, v107 row_shr:2 row_mask:0xf bank_mask:0xf bound_ctrl:1
	v_fmac_f32_dpp v238, v80, v108 row_shr:2 row_mask:0xf bank_mask:0xf bound_ctrl:1
	v_fmac_f32_dpp v239, v81, v109 row_shr:2 row_mask:0xf bank_mask:0xf bound_ctrl:1
	v_fmac_f32_dpp v240, v74, v110 row_shr:2 row_mask:0xf bank_mask:0xf bound_ctrl:1
	v_fmac_f32_dpp v241, v75, v111 row_shr:2 row_mask:0xf bank_mask:0xf bound_ctrl:1
	v_fmac_f32_dpp v242, v76, v112 row_shr:2 row_mask:0xf bank_mask:0xf bound_ctrl:1
	v_fmac_f32_dpp v243, v77, v113 row_shr:2 row_mask:0xf bank_mask:0xf bound_ctrl:1
	v_fmac_f32_dpp v236, v94, v114 row_shl:15 row_mask:0xf bank_mask:0xf bound_ctrl:1
	v_fmac_f32_dpp v237, v95, v115 row_shl:15 row_mask:0xf bank_mask:0xf bound_ctrl:1
	v_fmac_f32_dpp v238, v96, v116 row_shl:15 row_mask:0xf bank_mask:0xf bound_ctrl:1
	v_fmac_f32_dpp v239, v97, v117 row_shl:15 row_mask:0xf bank_mask:0xf bound_ctrl:1
	v_fmac_f32_dpp v240, v90, v118 row_shl:15 row_mask:0xf bank_mask:0xf bound_ctrl:1
	v_fmac_f32_dpp v241, v91, v119 row_shl:15 row_mask:0xf bank_mask:0xf bound_ctrl:1
	v_fmac_f32_dpp v242, v92, v120 row_shl:15 row_mask:0xf bank_mask:0xf bound_ctrl:1
	v_fmac_f32_dpp v243, v93, v121 row_shl:15 row_mask:0xf bank_mask:0xf bound_ctrl:1
	v_fmac_f32_dpp v236, v94, v106 row_shl:14 row_mask:0xf bank_mask:0xf bound_ctrl:1
	v_fmac_f32_dpp v237, v95, v107 row_shl:14 row_mask:0xf bank_mask:0xf bound_ctrl:1
	v_fmac_f32_dpp v238, v96, v108 row_shl:14 row_mask:0xf bank_mask:0xf bound_ctrl:1
	v_fmac_f32_dpp v239, v97, v109 row_shl:14 row_mask:0xf bank_mask:0xf bound_ctrl:1
	v_fmac_f32_dpp v240, v90, v110 row_shl:14 row_mask:0xf bank_mask:0xf bound_ctrl:1
	v_fmac_f32_dpp v241, v91, v111 row_shl:14 row_mask:0xf bank_mask:0xf bound_ctrl:1
	v_fmac_f32_dpp v242, v92, v112 row_shl:14 row_mask:0xf bank_mask:0xf bound_ctrl:1
	v_fmac_f32_dpp v243, v93, v113 row_shl:14 row_mask:0xf bank_mask:0xf bound_ctrl:1
	v_pk_mul_f32 v[244:245], v[236:237], s[92:93] op_sel_hi:[1,0]
	v_pk_mul_f32 v[246:247], v[238:239], s[92:93] op_sel_hi:[1,0]
	v_pk_mul_f32 v[248:249], v[240:241], s[92:93] op_sel_hi:[1,0]
	v_pk_mul_f32 v[250:251], v[242:243], s[92:93] op_sel_hi:[1,0]
	v_exp_f32_e32 v244, v244
	v_exp_f32_e32 v245, v245
	v_exp_f32_e32 v246, v246
	v_exp_f32_e32 v247, v247
	v_exp_f32_e32 v248, v248
	v_exp_f32_e32 v249, v249
	v_exp_f32_e32 v250, v250
	v_exp_f32_e32 v251, v251
	v_pk_mul_f32 v[236:237], v[236:237], v[70:71]
	v_pk_mul_f32 v[238:239], v[238:239], v[72:73]
	v_pk_mul_f32 v[240:241], v[240:241], v[66:67]
	v_pk_mul_f32 v[242:243], v[242:243], v[68:69]
	v_pk_add_f32 v[244:245], v[244:245], 1.0 op_sel_hi:[1,0]
	v_pk_add_f32 v[246:247], v[246:247], 1.0 op_sel_hi:[1,0]
	v_pk_add_f32 v[248:249], v[248:249], 1.0 op_sel_hi:[1,0]
	v_pk_add_f32 v[250:251], v[250:251], 1.0 op_sel_hi:[1,0]
	v_rcp_f32_e32 v244, v244
	v_rcp_f32_e32 v245, v245
	v_rcp_f32_e32 v246, v246
	v_rcp_f32_e32 v247, v247
	v_rcp_f32_e32 v248, v248
	v_rcp_f32_e32 v249, v249
	v_rcp_f32_e32 v250, v250
	v_rcp_f32_e32 v251, v251
	s_nop 0
	v_pk_mul_f32 v[236:237], v[236:237], v[244:245]
	v_pk_mul_f32 v[238:239], v[238:239], v[246:247]
	v_pk_mul_f32 v[240:241], v[240:241], v[248:249]
	v_pk_mul_f32 v[242:243], v[242:243], v[250:251]
	v_cvt_pk_bf16_f32 v216, v236, v237
	v_cvt_pk_bf16_f32 v217, v238, v239
	v_cvt_pk_bf16_f32 v218, v240, v241
	v_cvt_pk_bf16_f32 v219, v242, v243
	global_store_dwordx4 v[220:221], v[216:219], off sc1 nt
	v_lshl_add_u64 v[220:221], v[220:221], 0, s[98:99]
	v_pk_mul_f32 v[62:63], v[62:63], v[170:171] op_sel_hi:[1,0]
	v_pk_mul_f32 v[64:65], v[64:65], v[170:171] op_sel_hi:[1,0]
	v_pk_mul_f32 v[58:59], v[58:59], v[170:171] op_sel_hi:[1,0]
	v_pk_mul_f32 v[60:61], v[60:61], v[170:171] op_sel_hi:[1,0]
	v_lshl_add_u32 v167, v163, 2, s64
	ds_read_b128 v[192:195], v167
	ds_read_b128 v[196:199], v167 offset:16
	ds_read_b128 v[200:203], v167 offset:128
	ds_read_b128 v[204:207], v167 offset:144
	v_pk_fma_f32 v[236:237], v[122:123], v[62:63], v[130:131]
	v_pk_fma_f32 v[238:239], v[124:125], v[64:65], v[132:133]
	v_pk_fma_f32 v[240:241], v[126:127], v[58:59], v[134:135]
	v_pk_fma_f32 v[242:243], v[128:129], v[60:61], v[136:137]
	v_pk_mul_f32 v[54:55], v[54:55], v[170:171] op_sel_hi:[1,0]
;     __device__ __forceinline__ void operator()(const f32x4 (&acc)[2][2][4][2], const Unit& u, int wr, int wc, int fr, int fq) const {
;     ...
;             for (int m = 0; m < 4; ++m) {
;                 const int row = row0 + ai * HALF + m * 16; const float rs = rsv[m];
;                 const f32x4 ca = acc[ai][0][m][0] * rs, cb_ = acc[ai][0][m][1] * rs;
;                 f32x4 aa = w2a * ca + ba, ab = w2b * cb_ + bb;
; #pragma unroll
;                 for (int c = 0; c < 4; ++c) { aa[c] = __builtin_fmaf(w1a[c], dpp_shr1(ca[c]), aa[c]); ab[c] = __builtin_fmaf(w1b[c], dpp_shr1(cb_[c]), ab[c]);
;                     aa[c] = __builtin_fmaf(w0a[c], dpp_shr2(ca[c]), aa[c]); ab[c] = __builtin_fmaf(w0b[c], dpp_shr2(cb_[c]), ab[c]); }
;                 if (m == 0) {
;                     if (ai == 1 || wr == 1) { const int sw = ((ai == 1 && wr == 0) ? 4 : 0) + wc, sai = (ai == 1 && wr == 1) ? 1 : 0;
;                         const PG8_LAS f32x4* xp = (const PG8_LAS f32x4*)(X + ((sw * 2 + sai) * 2) * 32 + fq * 8); const f32x4 h0a = xp[0], h0b = xp[1], h1a = xp[8], h1b = xp[9];
;                         aa += w1a * (h1a * m0) + w0a * (h0a * m0 + h1a * m1); ab += w1b * (h1b * m0) + w0b * (h0b * m0 + h1b * m1); }
;                 } else {
; #pragma unroll
;                     for (int c = 0; c < 4; ++c) { aa[c] = __builtin_fmaf(w1a[c], dpp_shl15(pa[c]), aa[c]); ab[c] = __builtin_fmaf(w1b[c], dpp_shl15(pb[c]), ab[c]);
;                         aa[c] = __builtin_fmaf(w0a[c], dpp_shl14(pa[c]), aa[c]); ab[c] = __builtin_fmaf(w0b[c], dpp_shl14(pb[c]), ab[c]); }
;                 }
;                 const f32x4 ga = acc[ai][1][m][0] * rs, gb = acc[ai][1][m][1] * rs;
;                 f32x4 ea = aa * -1.4426950408889634f, eb = ab * -1.4426950408889634f;
; #pragma unroll
;                 for (int c = 0; c < 4; ++c) { ea[c] = __builtin_amdgcn_exp2f(ea[c]); eb[c] = __builtin_amdgcn_exp2f(eb[c]); }
;                 ea = ea + 1.0f; eb = eb + 1.0f;
; #pragma unroll
;                 for (int c = 0; c < 4; ++c) { ea[c] = __builtin_amdgcn_rcpf(ea[c]); eb[c] = __builtin_amdgcn_rcpf(eb[c]); }
;                 const f32x4 oa = (aa * ga) * ea, ob = (ab * gb) * eb;
;                 u32x4 w; w.x = cvt_pk_bf16(oa[0], oa[1]); w.y = cvt_pk_bf16(oa[2], oa[3]); w.z = cvt_pk_bf16(ob[0], ob[1]); w.w = cvt_pk_bf16(ob[2], ob[3]);
;                 *(u32x4*)(act + (size_t)row * FF + col) = w;
	v_pk_mul_f32 v[56:57], v[56:57], v[170:171] op_sel_hi:[1,0]
	v_pk_mul_f32 v[50:51], v[50:51], v[170:171] op_sel_hi:[1,0]
	v_pk_mul_f32 v[52:53], v[52:53], v[170:171] op_sel_hi:[1,0]
	v_fmac_f32_dpp v236, v62, v114 row_shr:1 row_mask:0xf bank_mask:0xf bound_ctrl:1
	v_fmac_f32_dpp v237, v63, v115 row_shr:1 row_mask:0xf bank_mask:0xf bound_ctrl:1
	v_fmac_f32_dpp v238, v64, v116 row_shr:1 row_mask:0xf bank_mask:0xf bound_ctrl:1
	v_fmac_f32_dpp v239, v65, v117 row_shr:1 row_mask:0xf bank_mask:0xf bound_ctrl:1
	v_fmac_f32_dpp v240, v58, v118 row_shr:1 row_mask:0xf bank_mask:0xf bound_ctrl:1
	v_fmac_f32_dpp v241, v59, v119 row_shr:1 row_mask:0xf bank_mask:0xf bound_ctrl:1
	v_fmac_f32_dpp v242, v60, v120 row_shr:1 row_mask:0xf bank_mask:0xf bound_ctrl:1
	v_fmac_f32_dpp v243, v61, v121 row_shr:1 row_mask:0xf bank_mask:0xf bound_ctrl:1
	v_fmac_f32_dpp v236, v62, v106 row_shr:2 row_mask:0xf bank_mask:0xf bound_ctrl:1
	v_fmac_f32_dpp v237, v63, v107 row_shr:2 row_mask:0xf bank_mask:0xf bound_ctrl:1
	v_fmac_f32_dpp v238, v64, v108 row_shr:2 row_mask:0xf bank_mask:0xf bound_ctrl:1
	v_fmac_f32_dpp v239, v65, v109 row_shr:2 row_mask:0xf bank_mask:0xf bound_ctrl:1
	v_fmac_f32_dpp v240, v58, v110 row_shr:2 row_mask:0xf bank_mask:0xf bound_ctrl:1
	v_fmac_f32_dpp v241, v59, v111 row_shr:2 row_mask:0xf bank_mask:0xf bound_ctrl:1
	v_fmac_f32_dpp v242, v60, v112 row_shr:2 row_mask:0xf bank_mask:0xf bound_ctrl:1
	v_fmac_f32_dpp v243, v61, v113 row_shr:2 row_mask:0xf bank_mask:0xf bound_ctrl:1
	v_cmp_eq_u32_e64 s[44:45], 0, v1
	v_cmp_eq_u32_e64 s[46:47], 1, v1
	s_waitcnt lgkmcnt(0)
	s_mov_b64 exec, s[44:45]
	v_pk_fma_f32 v[236:237], v[114:115], v[200:201], v[236:237]
	v_pk_fma_f32 v[238:239], v[116:117], v[202:203], v[238:239]
	v_pk_fma_f32 v[240:241], v[118:119], v[204:205], v[240:241]
	v_pk_fma_f32 v[242:243], v[120:121], v[206:207], v[242:243]
	v_pk_fma_f32 v[236:237], v[106:107], v[192:193], v[236:237]
	v_pk_fma_f32 v[238:239], v[108:109], v[194:195], v[238:239]
	v_pk_fma_f32 v[240:241], v[110:111], v[196:197], v[240:241]
	v_pk_fma_f32 v[242:243], v[112:113], v[198:199], v[242:243]
	s_mov_b64 exec, s[46:47]
	v_pk_fma_f32 v[236:237], v[106:107], v[200:201], v[236:237]
	v_pk_fma_f32 v[238:239], v[108:109], v[202:203], v[238:239]
	v_pk_fma_f32 v[240:241], v[110:111], v[204:205], v[240:241]
	v_pk_fma_f32 v[242:243], v[112:113], v[206:207], v[242:243]
	s_mov_b64 exec, -1
	v_pk_mul_f32 v[244:245], v[236:237], s[92:93] op_sel_hi:[1,0]
	v_pk_mul_f32 v[246:247], v[238:239], s[92:93] op_sel_hi:[1,0]
	v_pk_mul_f32 v[248:249], v[240:241], s[92:93] op_sel_hi:[1,0]
	v_pk_mul_f32 v[250:251], v[242:243], s[92:93] op_sel_hi:[1,0]
	v_exp_f32_e32 v244, v244
	v_exp_f32_e32 v245, v245
	v_exp_f32_e32 v246, v246
	v_exp_f32_e32 v247, v247
	v_exp_f32_e32 v248, v248
	v_exp_f32_e32 v249, v249
	v_exp_f32_e32 v250, v250
	v_exp_f32_e32 v251, v251
	v_pk_mul_f32 v[236:237], v[236:237], v[54:55]
	v_pk_mul_f32 v[238:239], v[238:239], v[56:57]
	v_pk_mul_f32 v[240:241], v[240:241], v[50:51]
	v_pk_mul_f32 v[242:243], v[242:243], v[52:53]
	v_pk_add_f32 v[244:245], v[244:245], 1.0 op_sel_hi:[1,0]
	v_pk_add_f32 v[246:247], v[246:247], 1.0 op_sel_hi:[1,0]
	v_pk_add_f32 v[248:249], v[248:249], 1.0 op_sel_hi:[1,0]
	v_pk_add_f32 v[250:251], v[250:251], 1.0 op_sel_hi:[1,0]
	v_rcp_f32_e32 v244, v244
	v_rcp_f32_e32 v245, v245
	v_rcp_f32_e32 v246, v246
	v_rcp_f32_e32 v247, v247
	v_rcp_f32_e32 v248, v248
	v_rcp_f32_e32 v249, v249
	v_rcp_f32_e32 v250, v250
	v_rcp_f32_e32 v251, v251
	s_nop 0
	v_pk_mul_f32 v[236:237], v[236:237], v[244:245]
	v_pk_mul_f32 v[238:239], v[238:239], v[246:247]
	v_pk_mul_f32 v[240:241], v[240:241], v[248:249]
	v_pk_mul_f32 v[242:243], v[242:243], v[250:251]
	v_cvt_pk_bf16_f32 v216, v236, v237
	v_cvt_pk_bf16_f32 v217, v238, v239
	v_cvt_pk_bf16_f32 v218, v240, v241
	v_cvt_pk_bf16_f32 v219, v242, v243
	global_store_dwordx4 v[220:221], v[216:219], off sc1 nt
	v_lshl_add_u64 v[220:221], v[220:221], 0, s[100:101]
	v_pk_mul_f32 v[46:47], v[46:47], v[172:173] op_sel_hi:[1,0]
	v_pk_mul_f32 v[48:49], v[48:49], v[172:173] op_sel_hi:[1,0]
	v_pk_mul_f32 v[42:43], v[42:43], v[172:173] op_sel_hi:[1,0]
	v_pk_mul_f32 v[44:45], v[44:45], v[172:173] op_sel_hi:[1,0]
	v_pk_fma_f32 v[236:237], v[122:123], v[46:47], v[130:131]
	v_pk_fma_f32 v[238:239], v[124:125], v[48:49], v[132:133]
	v_pk_fma_f32 v[240:241], v[126:127], v[42:43], v[134:135]
	v_pk_fma_f32 v[242:243], v[128:129], v[44:45], v[136:137]
	v_pk_mul_f32 v[38:39], v[38:39], v[172:173] op_sel_hi:[1,0]
	v_pk_mul_f32 v[40:41], v[40:41], v[172:173] op_sel_hi:[1,0]
	v_pk_mul_f32 v[34:35], v[34:35], v[172:173] op_sel_hi:[1,0]
	v_pk_mul_f32 v[36:37], v[36:37], v[172:173] op_sel_hi:[1,0]
	v_fmac_f32_dpp v236, v46, v114 row_shr:1 row_mask:0xf bank_mask:0xf bound_ctrl:1
	v_fmac_f32_dpp v237, v47, v115 row_shr:1 row_mask:0xf bank_mask:0xf bound_ctrl:1
	v_fmac_f32_dpp v238, v48, v116 row_shr:1 row_mask:0xf bank_mask:0xf bound_ctrl:1
	v_fmac_f32_dpp v239, v49, v117 row_shr:1 row_mask:0xf bank_mask:0xf bound_ctrl:1
	v_fmac_f32_dpp v240, v42, v118 row_shr:1 row_mask:0xf bank_mask:0xf bound_ctrl:1
	v_fmac_f32_dpp v241, v43, v119 row_shr:1 row_mask:0xf bank_mask:0xf bound_ctrl:1
	v_fmac_f32_dpp v242, v44, v120 row_shr:1 row_mask:0xf bank_mask:0xf bound_ctrl:1
	v_fmac_f32_dpp v243, v45, v121 row_shr:1 row_mask:0xf bank_mask:0xf bound_ctrl:1
	v_fmac_f32_dpp v236, v46, v106 row_shr:2 row_mask:0xf bank_mask:0xf bound_ctrl:1
	v_fmac_f32_dpp v237, v47, v107 row_shr:2 row_mask:0xf bank_mask:0xf bound_ctrl:1
	v_fmac_f32_dpp v238, v48, v108 row_shr:2 row_mask:0xf bank_mask:0xf bound_ctrl:1
	v_fmac_f32_dpp v239, v49, v109 row_shr:2 row_mask:0xf bank_mask:0xf bound_ctrl:1
;     __device__ __forceinline__ void operator()(const f32x4 (&acc)[2][2][4][2], const Unit& u, int wr, int wc, int fr, int fq) const {
;     ...
;             for (int m = 0; m < 4; ++m) {
;                 const int row = row0 + ai * HALF + m * 16; const float rs = rsv[m];
;                 const f32x4 ca = acc[ai][0][m][0] * rs, cb_ = acc[ai][0][m][1] * rs;
;                 f32x4 aa = w2a * ca + ba, ab = w2b * cb_ + bb;
; #pragma unroll
;                 for (int c = 0; c < 4; ++c) { aa[c] = __builtin_fmaf(w1a[c], dpp_shr1(ca[c]), aa[c]); ab[c] = __builtin_fmaf(w1b[c], dpp_shr1(cb_[c]), ab[c]);
;                     aa[c] = __builtin_fmaf(w0a[c], dpp_shr2(ca[c]), aa[c]); ab[c] = __builtin_fmaf(w0b[c], dpp_shr2(cb_[c]), ab[c]); }
;                 if (m == 0) {
;                     if (ai == 1 || wr == 1) { const int sw = ((ai == 1 && wr == 0) ? 4 : 0) + wc, sai = (ai == 1 && wr == 1) ? 1 : 0;
;                         const PG8_LAS f32x4* xp = (const PG8_LAS f32x4*)(X + ((sw * 2 + sai) * 2) * 32 + fq * 8); const f32x4 h0a = xp[0], h0b = xp[1], h1a = xp[8], h1b = xp[9];
;                         aa += w1a * (h1a * m0) + w0a * (h0a * m0 + h1a * m1); ab += w1b * (h1b * m0) + w0b * (h0b * m0 + h1b * m1); }
;                 } else {
; #pragma unroll
;                     for (int c = 0; c < 4; ++c) { aa[c] = __builtin_fmaf(w1a[c], dpp_shl15(pa[c]), aa[c]); ab[c] = __builtin_fmaf(w1b[c], dpp_shl15(pb[c]), ab[c]);
;                         aa[c] = __builtin_fmaf(w0a[c], dpp_shl14(pa[c]), aa[c]); ab[c] = __builtin_fmaf(w0b[c], dpp_shl14(pb[c]), ab[c]); }
;                 }
;                 const f32x4 ga = acc[ai][1][m][0] * rs, gb = acc[ai][1][m][1] * rs;
;                 f32x4 ea = aa * -1.4426950408889634f, eb = ab * -1.4426950408889634f;
; #pragma unroll
;                 for (int c = 0; c < 4; ++c) { ea[c] = __builtin_amdgcn_exp2f(ea[c]); eb[c] = __builtin_amdgcn_exp2f(eb[c]); }
;                 ea = ea + 1.0f; eb = eb + 1.0f;
; #pragma unroll
;                 for (int c = 0; c < 4; ++c) { ea[c] = __builtin_amdgcn_rcpf(ea[c]); eb[c] = __builtin_amdgcn_rcpf(eb[c]); }
;                 const f32x4 oa = (aa * ga) * ea, ob = (ab * gb) * eb;
;                 u32x4 w; w.x = cvt_pk_bf16(oa[0], oa[1]); w.y = cvt_pk_bf16(oa[2], oa[3]); w.z = cvt_pk_bf16(ob[0], ob[1]); w.w = cvt_pk_bf16(ob[2], ob[3]);
;                 *(u32x4*)(act + (size_t)row * FF + col) = w;
	v_fmac_f32_dpp v240, v42, v110 row_shr:2 row_mask:0xf bank_mask:0xf bound_ctrl:1
	v_fmac_f32_dpp v241, v43, v111 row_shr:2 row_mask:0xf bank_mask:0xf bound_ctrl:1
	v_fmac_f32_dpp v242, v44, v112 row_shr:2 row_mask:0xf bank_mask:0xf bound_ctrl:1
	v_fmac_f32_dpp v243, v45, v113 row_shr:2 row_mask:0xf bank_mask:0xf bound_ctrl:1
	v_fmac_f32_dpp v236, v62, v114 row_shl:15 row_mask:0xf bank_mask:0xf bound_ctrl:1
	v_fmac_f32_dpp v237, v63, v115 row_shl:15 row_mask:0xf bank_mask:0xf bound_ctrl:1
	v_fmac_f32_dpp v238, v64, v116 row_shl:15 row_mask:0xf bank_mask:0xf bound_ctrl:1
	v_fmac_f32_dpp v239, v65, v117 row_shl:15 row_mask:0xf bank_mask:0xf bound_ctrl:1
	v_fmac_f32_dpp v240, v58, v118 row_shl:15 row_mask:0xf bank_mask:0xf bound_ctrl:1
	v_fmac_f32_dpp v241, v59, v119 row_shl:15 row_mask:0xf bank_mask:0xf bound_ctrl:1
	v_fmac_f32_dpp v242, v60, v120 row_shl:15 row_mask:0xf bank_mask:0xf bound_ctrl:1
	v_fmac_f32_dpp v243, v61, v121 row_shl:15 row_mask:0xf bank_mask:0xf bound_ctrl:1
	v_fmac_f32_dpp v236, v62, v106 row_shl:14 row_mask:0xf bank_mask:0xf bound_ctrl:1
	v_fmac_f32_dpp v237, v63, v107 row_shl:14 row_mask:0xf bank_mask:0xf bound_ctrl:1
	v_fmac_f32_dpp v238, v64, v108 row_shl:14 row_mask:0xf bank_mask:0xf bound_ctrl:1
	v_fmac_f32_dpp v239, v65, v109 row_shl:14 row_mask:0xf bank_mask:0xf bound_ctrl:1
	v_fmac_f32_dpp v240, v58, v110 row_shl:14 row_mask:0xf bank_mask:0xf bound_ctrl:1
	v_fmac_f32_dpp v241, v59, v111 row_shl:14 row_mask:0xf bank_mask:0xf bound_ctrl:1
	v_fmac_f32_dpp v242, v60, v112 row_shl:14 row_mask:0xf bank_mask:0xf bound_ctrl:1
	v_fmac_f32_dpp v243, v61, v113 row_shl:14 row_mask:0xf bank_mask:0xf bound_ctrl:1
	v_pk_mul_f32 v[244:245], v[236:237], s[92:93] op_sel_hi:[1,0]
	v_pk_mul_f32 v[246:247], v[238:239], s[92:93] op_sel_hi:[1,0]
	v_pk_mul_f32 v[248:249], v[240:241], s[92:93] op_sel_hi:[1,0]
	v_pk_mul_f32 v[250:251], v[242:243], s[92:93] op_sel_hi:[1,0]
	v_exp_f32_e32 v244, v244
	v_exp_f32_e32 v245, v245
	v_exp_f32_e32 v246, v246
	v_exp_f32_e32 v247, v247
	v_exp_f32_e32 v248, v248
	v_exp_f32_e32 v249, v249
	v_exp_f32_e32 v250, v250
	v_exp_f32_e32 v251, v251
	v_pk_mul_f32 v[236:237], v[236:237], v[38:39]
	v_pk_mul_f32 v[238:239], v[238:239], v[40:41]
	v_pk_mul_f32 v[240:241], v[240:241], v[34:35]
	v_pk_mul_f32 v[242:243], v[242:243], v[36:37]
	v_pk_add_f32 v[244:245], v[244:245], 1.0 op_sel_hi:[1,0]
	v_pk_add_f32 v[246:247], v[246:247], 1.0 op_sel_hi:[1,0]
	v_pk_add_f32 v[248:249], v[248:249], 1.0 op_sel_hi:[1,0]
	v_pk_add_f32 v[250:251], v[250:251], 1.0 op_sel_hi:[1,0]
	v_rcp_f32_e32 v244, v244
	v_rcp_f32_e32 v245, v245
	v_rcp_f32_e32 v246, v246
	v_rcp_f32_e32 v247, v247
	v_rcp_f32_e32 v248, v248
	v_rcp_f32_e32 v249, v249
	v_rcp_f32_e32 v250, v250
	v_rcp_f32_e32 v251, v251
	s_nop 0
	v_pk_mul_f32 v[236:237], v[236:237], v[244:245]
	v_pk_mul_f32 v[238:239], v[238:239], v[246:247]
	v_pk_mul_f32 v[240:241], v[240:241], v[248:249]
	v_pk_mul_f32 v[242:243], v[242:243], v[250:251]
	v_cvt_pk_bf16_f32 v216, v236, v237
	v_cvt_pk_bf16_f32 v217, v238, v239
	v_cvt_pk_bf16_f32 v218, v240, v241
	v_cvt_pk_bf16_f32 v219, v242, v243
	global_store_dwordx4 v[220:221], v[216:219], off sc1 nt
	v_lshl_add_u64 v[220:221], v[220:221], 0, s[100:101]
	v_pk_mul_f32 v[30:31], v[30:31], v[232:233] op_sel_hi:[1,0]
	v_pk_mul_f32 v[32:33], v[32:33], v[232:233] op_sel_hi:[1,0]
	v_pk_mul_f32 v[26:27], v[26:27], v[232:233] op_sel_hi:[1,0]
	v_pk_mul_f32 v[28:29], v[28:29], v[232:233] op_sel_hi:[1,0]
	v_pk_fma_f32 v[236:237], v[122:123], v[30:31], v[130:131]
	v_pk_fma_f32 v[238:239], v[124:125], v[32:33], v[132:133]
	v_pk_fma_f32 v[240:241], v[126:127], v[26:27], v[134:135]
	v_pk_fma_f32 v[242:243], v[128:129], v[28:29], v[136:137]
	v_pk_mul_f32 v[22:23], v[22:23], v[232:233] op_sel_hi:[1,0]
	v_pk_mul_f32 v[24:25], v[24:25], v[232:233] op_sel_hi:[1,0]
	v_pk_mul_f32 v[18:19], v[18:19], v[232:233] op_sel_hi:[1,0]
	v_pk_mul_f32 v[20:21], v[20:21], v[232:233] op_sel_hi:[1,0]
	v_fmac_f32_dpp v236, v30, v114 row_shr:1 row_mask:0xf bank_mask:0xf bound_ctrl:1
	v_fmac_f32_dpp v237, v31, v115 row_shr:1 row_mask:0xf bank_mask:0xf bound_ctrl:1
	v_fmac_f32_dpp v238, v32, v116 row_shr:1 row_mask:0xf bank_mask:0xf bound_ctrl:1
	v_fmac_f32_dpp v239, v33, v117 row_shr:1 row_mask:0xf bank_mask:0xf bound_ctrl:1
	v_fmac_f32_dpp v240, v26, v118 row_shr:1 row_mask:0xf bank_mask:0xf bound_ctrl:1
	v_fmac_f32_dpp v241, v27, v119 row_shr:1 row_mask:0xf bank_mask:0xf bound_ctrl:1
	v_fmac_f32_dpp v242, v28, v120 row_shr:1 row_mask:0xf bank_mask:0xf bound_ctrl:1
	v_fmac_f32_dpp v243, v29, v121 row_shr:1 row_mask:0xf bank_mask:0xf bound_ctrl:1
	v_fmac_f32_dpp v236, v30, v106 row_shr:2 row_mask:0xf bank_mask:0xf bound_ctrl:1
	v_fmac_f32_dpp v237, v31, v107 row_shr:2 row_mask:0xf bank_mask:0xf bound_ctrl:1
	v_fmac_f32_dpp v238, v32, v108 row_shr:2 row_mask:0xf bank_mask:0xf bound_ctrl:1
	v_fmac_f32_dpp v239, v33, v109 row_shr:2 row_mask:0xf bank_mask:0xf bound_ctrl:1
	v_fmac_f32_dpp v240, v26, v110 row_shr:2 row_mask:0xf bank_mask:0xf bound_ctrl:1
	v_fmac_f32_dpp v241, v27, v111 row_shr:2 row_mask:0xf bank_mask:0xf bound_ctrl:1
	v_fmac_f32_dpp v242, v28, v112 row_shr:2 row_mask:0xf bank_mask:0xf bound_ctrl:1
	v_fmac_f32_dpp v243, v29, v113 row_shr:2 row_mask:0xf bank_mask:0xf bound_ctrl:1
	v_fmac_f32_dpp v236, v46, v114 row_shl:15 row_mask:0xf bank_mask:0xf bound_ctrl:1
	v_fmac_f32_dpp v237, v47, v115 row_shl:15 row_mask:0xf bank_mask:0xf bound_ctrl:1
	v_fmac_f32_dpp v238, v48, v116 row_shl:15 row_mask:0xf bank_mask:0xf bound_ctrl:1
	v_fmac_f32_dpp v239, v49, v117 row_shl:15 row_mask:0xf bank_mask:0xf bound_ctrl:1
	v_fmac_f32_dpp v240, v42, v118 row_shl:15 row_mask:0xf bank_mask:0xf bound_ctrl:1
;     __device__ __forceinline__ void operator()(const f32x4 (&acc)[2][2][4][2], const Unit& u, int wr, int wc, int fr, int fq) const {
;     ...
;             for (int m = 0; m < 4; ++m) {
;                 const int row = row0 + ai * HALF + m * 16; const float rs = rsv[m];
;                 const f32x4 ca = acc[ai][0][m][0] * rs, cb_ = acc[ai][0][m][1] * rs;
;                 f32x4 aa = w2a * ca + ba, ab = w2b * cb_ + bb;
; #pragma unroll
;                 for (int c = 0; c < 4; ++c) { aa[c] = __builtin_fmaf(w1a[c], dpp_shr1(ca[c]), aa[c]); ab[c] = __builtin_fmaf(w1b[c], dpp_shr1(cb_[c]), ab[c]);
;                     aa[c] = __builtin_fmaf(w0a[c], dpp_shr2(ca[c]), aa[c]); ab[c] = __builtin_fmaf(w0b[c], dpp_shr2(cb_[c]), ab[c]); }
;                 if (m == 0) {
;                     if (ai == 1 || wr == 1) { const int sw = ((ai == 1 && wr == 0) ? 4 : 0) + wc, sai = (ai == 1 && wr == 1) ? 1 : 0;
;                         const PG8_LAS f32x4* xp = (const PG8_LAS f32x4*)(X + ((sw * 2 + sai) * 2) * 32 + fq * 8); const f32x4 h0a = xp[0], h0b = xp[1], h1a = xp[8], h1b = xp[9];
;                         aa += w1a * (h1a * m0) + w0a * (h0a * m0 + h1a * m1); ab += w1b * (h1b * m0) + w0b * (h0b * m0 + h1b * m1); }
;                 } else {
; #pragma unroll
;                     for (int c = 0; c < 4; ++c) { aa[c] = __builtin_fmaf(w1a[c], dpp_shl15(pa[c]), aa[c]); ab[c] = __builtin_fmaf(w1b[c], dpp_shl15(pb[c]), ab[c]);
;                         aa[c] = __builtin_fmaf(w0a[c], dpp_shl14(pa[c]), aa[c]); ab[c] = __builtin_fmaf(w0b[c], dpp_shl14(pb[c]), ab[c]); }
;                 }
;                 const f32x4 ga = acc[ai][1][m][0] * rs, gb = acc[ai][1][m][1] * rs;
;                 f32x4 ea = aa * -1.4426950408889634f, eb = ab * -1.4426950408889634f;
; #pragma unroll
;                 for (int c = 0; c < 4; ++c) { ea[c] = __builtin_amdgcn_exp2f(ea[c]); eb[c] = __builtin_amdgcn_exp2f(eb[c]); }
;                 ea = ea + 1.0f; eb = eb + 1.0f;
; #pragma unroll
;                 for (int c = 0; c < 4; ++c) { ea[c] = __builtin_amdgcn_rcpf(ea[c]); eb[c] = __builtin_amdgcn_rcpf(eb[c]); }
;                 const f32x4 oa = (aa * ga) * ea, ob = (ab * gb) * eb;
;                 u32x4 w; w.x = cvt_pk_bf16(oa[0], oa[1]); w.y = cvt_pk_bf16(oa[2], oa[3]); w.z = cvt_pk_bf16(ob[0], ob[1]); w.w = cvt_pk_bf16(ob[2], ob[3]);
;                 *(u32x4*)(act + (size_t)row * FF + col) = w;
	v_fmac_f32_dpp v241, v43, v119 row_shl:15 row_mask:0xf bank_mask:0xf bound_ctrl:1
	v_fmac_f32_dpp v242, v44, v120 row_shl:15 row_mask:0xf bank_mask:0xf bound_ctrl:1
	v_fmac_f32_dpp v243, v45, v121 row_shl:15 row_mask:0xf bank_mask:0xf bound_ctrl:1
	v_fmac_f32_dpp v236, v46, v106 row_shl:14 row_mask:0xf bank_mask:0xf bound_ctrl:1
	v_fmac_f32_dpp v237, v47, v107 row_shl:14 row_mask:0xf bank_mask:0xf bound_ctrl:1
	v_fmac_f32_dpp v238, v48, v108 row_shl:14 row_mask:0xf bank_mask:0xf bound_ctrl:1
	v_fmac_f32_dpp v239, v49, v109 row_shl:14 row_mask:0xf bank_mask:0xf bound_ctrl:1
	v_fmac_f32_dpp v240, v42, v110 row_shl:14 row_mask:0xf bank_mask:0xf bound_ctrl:1
	v_fmac_f32_dpp v241, v43, v111 row_shl:14 row_mask:0xf bank_mask:0xf bound_ctrl:1
	v_fmac_f32_dpp v242, v44, v112 row_shl:14 row_mask:0xf bank_mask:0xf bound_ctrl:1
	v_fmac_f32_dpp v243, v45, v113 row_shl:14 row_mask:0xf bank_mask:0xf bound_ctrl:1
	v_pk_mul_f32 v[244:245], v[236:237], s[92:93] op_sel_hi:[1,0]
	v_pk_mul_f32 v[246:247], v[238:239], s[92:93] op_sel_hi:[1,0]
	v_pk_mul_f32 v[248:249], v[240:241], s[92:93] op_sel_hi:[1,0]
	v_pk_mul_f32 v[250:251], v[242:243], s[92:93] op_sel_hi:[1,0]
	v_exp_f32_e32 v244, v244
	v_exp_f32_e32 v245, v245
	v_exp_f32_e32 v246, v246
	v_exp_f32_e32 v247, v247
	v_exp_f32_e32 v248, v248
	v_exp_f32_e32 v249, v249
	v_exp_f32_e32 v250, v250
	v_exp_f32_e32 v251, v251
	v_pk_mul_f32 v[236:237], v[236:237], v[22:23]
	v_pk_mul_f32 v[238:239], v[238:239], v[24:25]
	v_pk_mul_f32 v[240:241], v[240:241], v[18:19]
	v_pk_mul_f32 v[242:243], v[242:243], v[20:21]
	v_pk_add_f32 v[244:245], v[244:245], 1.0 op_sel_hi:[1,0]
	v_pk_add_f32 v[246:247], v[246:247], 1.0 op_sel_hi:[1,0]
	v_pk_add_f32 v[248:249], v[248:249], 1.0 op_sel_hi:[1,0]
	v_pk_add_f32 v[250:251], v[250:251], 1.0 op_sel_hi:[1,0]
	v_rcp_f32_e32 v244, v244
	v_rcp_f32_e32 v245, v245
	v_rcp_f32_e32 v246, v246
	v_rcp_f32_e32 v247, v247
	v_rcp_f32_e32 v248, v248
	v_rcp_f32_e32 v249, v249
	v_rcp_f32_e32 v250, v250
	v_rcp_f32_e32 v251, v251
	s_nop 0
	v_pk_mul_f32 v[236:237], v[236:237], v[244:245]
	v_pk_mul_f32 v[238:239], v[238:239], v[246:247]
	v_pk_mul_f32 v[240:241], v[240:241], v[248:249]
	v_pk_mul_f32 v[242:243], v[242:243], v[250:251]
	v_cvt_pk_bf16_f32 v216, v236, v237
	v_cvt_pk_bf16_f32 v217, v238, v239
	v_cvt_pk_bf16_f32 v218, v240, v241
	v_cvt_pk_bf16_f32 v219, v242, v243
	global_store_dwordx4 v[220:221], v[216:219], off sc1 nt
	v_lshl_add_u64 v[220:221], v[220:221], 0, s[100:101]
	v_pk_fma_f32 v[236:237], v[122:123], v[14:15], v[130:131]
	v_pk_fma_f32 v[238:239], v[124:125], v[16:17], v[132:133]
	v_pk_fma_f32 v[240:241], v[126:127], v[10:11], v[134:135]
	v_pk_fma_f32 v[242:243], v[128:129], v[12:13], v[136:137]
	v_pk_mul_f32 v[6:7], v[6:7], v[234:235] op_sel_hi:[1,0]
	v_pk_mul_f32 v[8:9], v[8:9], v[234:235] op_sel_hi:[1,0]
	v_pk_mul_f32 v[2:3], v[2:3], v[234:235] op_sel_hi:[1,0]
	v_pk_mul_f32 v[4:5], v[4:5], v[234:235] op_sel_hi:[1,0]
	v_fmac_f32_dpp v236, v14, v114 row_shr:1 row_mask:0xf bank_mask:0xf bound_ctrl:1
	v_fmac_f32_dpp v237, v15, v115 row_shr:1 row_mask:0xf bank_mask:0xf bound_ctrl:1
	v_fmac_f32_dpp v238, v16, v116 row_shr:1 row_mask:0xf bank_mask:0xf bound_ctrl:1
	v_fmac_f32_dpp v239, v17, v117 row_shr:1 row_mask:0xf bank_mask:0xf bound_ctrl:1
	v_fmac_f32_dpp v240, v10, v118 row_shr:1 row_mask:0xf bank_mask:0xf bound_ctrl:1
	v_fmac_f32_dpp v241, v11, v119 row_shr:1 row_mask:0xf bank_mask:0xf bound_ctrl:1
	v_fmac_f32_dpp v242, v12, v120 row_shr:1 row_mask:0xf bank_mask:0xf bound_ctrl:1
	v_fmac_f32_dpp v243, v13, v121 row_shr:1 row_mask:0xf bank_mask:0xf bound_ctrl:1
	v_fmac_f32_dpp v236, v14, v106 row_shr:2 row_mask:0xf bank_mask:0xf bound_ctrl:1
;     __device__ __forceinline__ void operator()(const f32x4 (&acc)[2][2][4][2], const Unit& u, int wr, int wc, int fr, int fq) const {
;     ...
;             for (int m = 0; m < 4; ++m) {
;                 const int row = row0 + ai * HALF + m * 16; const float rs = rsv[m];
;                 const f32x4 ca = acc[ai][0][m][0] * rs, cb_ = acc[ai][0][m][1] * rs;
;                 f32x4 aa = w2a * ca + ba, ab = w2b * cb_ + bb;
; #pragma unroll
;                 for (int c = 0; c < 4; ++c) { aa[c] = __builtin_fmaf(w1a[c], dpp_shr1(ca[c]), aa[c]); ab[c] = __builtin_fmaf(w1b[c], dpp_shr1(cb_[c]), ab[c]);
;                     aa[c] = __builtin_fmaf(w0a[c], dpp_shr2(ca[c]), aa[c]); ab[c] = __builtin_fmaf(w0b[c], dpp_shr2(cb_[c]), ab[c]); }
;                 if (m == 0) {
;                     if (ai == 1 || wr == 1) { const int sw = ((ai == 1 && wr == 0) ? 4 : 0) + wc, sai = (ai == 1 && wr == 1) ? 1 : 0;
;                         const PG8_LAS f32x4* xp = (const PG8_LAS f32x4*)(X + ((sw * 2 + sai) * 2) * 32 + fq * 8); const f32x4 h0a = xp[0], h0b = xp[1], h1a = xp[8], h1b = xp[9];
;                         aa += w1a * (h1a * m0) + w0a * (h0a * m0 + h1a * m1); ab += w1b * (h1b * m0) + w0b * (h0b * m0 + h1b * m1); }
;                 } else {
; #pragma unroll
;                     for (int c = 0; c < 4; ++c) { aa[c] = __builtin_fmaf(w1a[c], dpp_shl15(pa[c]), aa[c]); ab[c] = __builtin_fmaf(w1b[c], dpp_shl15(pb[c]), ab[c]);
;                         aa[c] = __builtin_fmaf(w0a[c], dpp_shl14(pa[c]), aa[c]); ab[c] = __builtin_fmaf(w0b[c], dpp_shl14(pb[c]), ab[c]); }
;                 }
;                 const f32x4 ga = acc[ai][1][m][0] * rs, gb = acc[ai][1][m][1] * rs;
;                 f32x4 ea = aa * -1.4426950408889634f, eb = ab * -1.4426950408889634f;
; #pragma unroll
;                 for (int c = 0; c < 4; ++c) { ea[c] = __builtin_amdgcn_exp2f(ea[c]); eb[c] = __builtin_amdgcn_exp2f(eb[c]); }
;                 ea = ea + 1.0f; eb = eb + 1.0f;
; #pragma unroll
;                 for (int c = 0; c < 4; ++c) { ea[c] = __builtin_amdgcn_rcpf(ea[c]); eb[c] = __builtin_amdgcn_rcpf(eb[c]); }
;                 const f32x4 oa = (aa * ga) * ea, ob = (ab * gb) * eb;
;                 u32x4 w; w.x = cvt_pk_bf16(oa[0], oa[1]); w.y = cvt_pk_bf16(oa[2], oa[3]); w.z = cvt_pk_bf16(ob[0], ob[1]); w.w = cvt_pk_bf16(ob[2], ob[3]);
;                 *(u32x4*)(act + (size_t)row * FF + col) = w;
	v_fmac_f32_dpp v237, v15, v107 row_shr:2 row_mask:0xf bank_mask:0xf bound_ctrl:1
	v_fmac_f32_dpp v238, v16, v108 row_shr:2 row_mask:0xf bank_mask:0xf bound_ctrl:1
	v_fmac_f32_dpp v239, v17, v109 row_shr:2 row_mask:0xf bank_mask:0xf bound_ctrl:1
	v_fmac_f32_dpp v240, v10, v110 row_shr:2 row_mask:0xf bank_mask:0xf bound_ctrl:1
	v_fmac_f32_dpp v241, v11, v111 row_shr:2 row_mask:0xf bank_mask:0xf bound_ctrl:1
	v_fmac_f32_dpp v242, v12, v112 row_shr:2 row_mask:0xf bank_mask:0xf bound_ctrl:1
	v_fmac_f32_dpp v243, v13, v113 row_shr:2 row_mask:0xf bank_mask:0xf bound_ctrl:1
	v_fmac_f32_dpp v236, v30, v114 row_shl:15 row_mask:0xf bank_mask:0xf bound_ctrl:1
	v_fmac_f32_dpp v237, v31, v115 row_shl:15 row_mask:0xf bank_mask:0xf bound_ctrl:1
	v_fmac_f32_dpp v238, v32, v116 row_shl:15 row_mask:0xf bank_mask:0xf bound_ctrl:1
	v_fmac_f32_dpp v239, v33, v117 row_shl:15 row_mask:0xf bank_mask:0xf bound_ctrl:1
	v_fmac_f32_dpp v240, v26, v118 row_shl:15 row_mask:0xf bank_mask:0xf bound_ctrl:1
	v_fmac_f32_dpp v241, v27, v119 row_shl:15 row_mask:0xf bank_mask:0xf bound_ctrl:1
	v_fmac_f32_dpp v242, v28, v120 row_shl:15 row_mask:0xf bank_mask:0xf bound_ctrl:1
	v_fmac_f32_dpp v243, v29, v121 row_shl:15 row_mask:0xf bank_mask:0xf bound_ctrl:1
	v_fmac_f32_dpp v236, v30, v106 row_shl:14 row_mask:0xf bank_mask:0xf bound_ctrl:1
	v_fmac_f32_dpp v237, v31, v107 row_shl:14 row_mask:0xf bank_mask:0xf bound_ctrl:1
	v_fmac_f32_dpp v238, v32, v108 row_shl:14 row_mask:0xf bank_mask:0xf bound_ctrl:1
	v_fmac_f32_dpp v239, v33, v109 row_shl:14 row_mask:0xf bank_mask:0xf bound_ctrl:1
	v_fmac_f32_dpp v240, v26, v110 row_shl:14 row_mask:0xf bank_mask:0xf bound_ctrl:1
	v_fmac_f32_dpp v241, v27, v111 row_shl:14 row_mask:0xf bank_mask:0xf bound_ctrl:1
	v_fmac_f32_dpp v242, v28, v112 row_shl:14 row_mask:0xf bank_mask:0xf bound_ctrl:1
	v_fmac_f32_dpp v243, v29, v113 row_shl:14 row_mask:0xf bank_mask:0xf bound_ctrl:1
	v_pk_mul_f32 v[244:245], v[236:237], s[92:93] op_sel_hi:[1,0]
	v_pk_mul_f32 v[246:247], v[238:239], s[92:93] op_sel_hi:[1,0]
	v_pk_mul_f32 v[248:249], v[240:241], s[92:93] op_sel_hi:[1,0]
	v_pk_mul_f32 v[250:251], v[242:243], s[92:93] op_sel_hi:[1,0]
	v_exp_f32_e32 v244, v244
	v_exp_f32_e32 v245, v245
	v_exp_f32_e32 v246, v246
	v_exp_f32_e32 v247, v247
	v_exp_f32_e32 v248, v248
	v_exp_f32_e32 v249, v249
	v_exp_f32_e32 v250, v250
	v_exp_f32_e32 v251, v251
	v_pk_mul_f32 v[236:237], v[236:237], v[6:7]
	v_pk_mul_f32 v[238:239], v[238:239], v[8:9]
	v_pk_mul_f32 v[240:241], v[240:241], v[2:3]
	v_pk_mul_f32 v[242:243], v[242:243], v[4:5]
	v_pk_add_f32 v[244:245], v[244:245], 1.0 op_sel_hi:[1,0]
	v_pk_add_f32 v[246:247], v[246:247], 1.0 op_sel_hi:[1,0]
	v_pk_add_f32 v[248:249], v[248:249], 1.0 op_sel_hi:[1,0]
	v_pk_add_f32 v[250:251], v[250:251], 1.0 op_sel_hi:[1,0]
	v_rcp_f32_e32 v244, v244
	v_rcp_f32_e32 v245, v245
	v_rcp_f32_e32 v246, v246
	v_rcp_f32_e32 v247, v247
	v_rcp_f32_e32 v248, v248
	v_rcp_f32_e32 v249, v249
	v_rcp_f32_e32 v250, v250
	v_rcp_f32_e32 v251, v251
	s_nop 0
	v_pk_mul_f32 v[236:237], v[236:237], v[244:245]
	v_pk_mul_f32 v[238:239], v[238:239], v[246:247]
	v_pk_mul_f32 v[240:241], v[240:241], v[248:249]
	v_pk_mul_f32 v[242:243], v[242:243], v[250:251]
	v_cvt_pk_bf16_f32 v216, v236, v237
	v_cvt_pk_bf16_f32 v217, v238, v239
	v_cvt_pk_bf16_f32 v218, v240, v241
	v_cvt_pk_bf16_f32 v219, v242, v243
	global_store_dwordx4 v[220:221], v[216:219], off sc1 nt
	s_mov_b64 s[66:67], 0x8000
	s_andn2_b64 vcc, exec, s[6:7]
	s_mov_b64 s[6:7], -1
	s_not_b64 s[8:9], s[4:5]
	s_cbranch_vccnz .LBB0_1243
	s_and_b64 vcc, exec, s[8:9]
	s_cbranch_vccnz .LBB0_1242
	s_barrier
	s_branch .LBB0_1242
